# combo4 + ph8/ph15 order swap: workgroups >=128 run the PP GEMM before the down GEMM (desynchronised epilogue bursts)
# baseline (speedup 1.0000x reference)
.LBB0_752:
	s_cmp_lt_i32 s80, 9
	s_cselect_b64 s[0:1], -1, 0
	s_cmp_gt_i32 s81, 8
	s_cselect_b64 s[2:3], -1, 0
	s_and_b64 s[0:1], s[0:1], s[2:3]
	s_andn2_b64 vcc, exec, s[0:1]
	s_cbranch_vccnz .LBB0_882
	s_mov_b32 s99, 0
	s_cmp_eq_u32 s82, 0x100
	s_cbranch_scc0 .Lsw8_top
	s_cmp_lt_u32 s96, 0x80
	s_cbranch_scc1 .Lsw8_top
	s_mov_b32 s99, 1

; #define PG8_STAGE(bufoff, gbase, voff) do { _Pragma("unroll") for (int _i = 0; _i < 2; ++_i) \
;         __builtin_amdgcn_global_load_lds((const unsigned*)((const char*)(gbase) + (voff)[_i]), (PG8_LAS unsigned*)(lds + (bufoff) + ldsw + _i * 8192), 16, 0, 0); } while (0)
; #define PG8_BAR __builtin_amdgcn_s_barrier()
; template <class Epi, class Sched, bool ALIGN_EPI = false, bool SP2 = false>
; __device__ __forceinline__ void gemm_phase(PG8_LAS unsigned char* lds, const Gemm g, const Sched& S, const Epi& E) {
;     int tid_ = threadIdx.x; asm volatile("" : "+v"(tid_));
;     const int tid = tid_, wid = __builtin_amdgcn_readfirstlane(tid >> 6), lane = tid & 63, wr = wid >> 2, wc = wid & 3, fr = lane & 15, fq = lane >> 4;
;     const int K = g.K, nt = K / BK;
;     unsigned voffA[2], voffB[2];
; #pragma unroll
;     for (int i = 0; i < 2; ++i) { int R, C; stage_rc(tid * 16 + i * 8192, R, C); const int Rb = Epi::PERM ? ((R & ~31) + perm32(R & 31)) : R;
;         voffA[i] = (unsigned)(R * g.lda + C) * 2u; voffB[i] = (unsigned)(Rb * g.ldb + C) * 2u; }
;     const size_t kstep = (size_t)(BK * 2);
;     const size_t hstepA = (size_t)HALF * g.lda * 2, hstepB = (size_t)HALF * g.ldb * 2;
;     const size_t tstepA = 2 * hstepA, tstepB = 2 * hstepB;
;     const unsigned ldsw = (unsigned)wid * 1024u;
;     const int aoff = lds_byte(wr * 64 + fr, fq * 8), boff = lds_byte(wc * 32 + fr, fq * 8);
;     ...
;     Unit cur, nxt; int ui = 0;
;     if (!S.next(0, cur)) return;
;     f32x4 acc[2][2][4][2];
; #pragma unroll
;     for (int a = 0; a < 2; ++a)
; #pragma unroll
;         for (int b = 0; b < 2; ++b)
; #pragma unroll
;             for (int m = 0; m < 4; ++m)
; #pragma unroll
;                 for (int n = 0; n < 2; ++n) acc[a][b][m][n] = (f32x4){0.f, 0.f, 0.f, 0.f};
;     bf16x8 At[4][2], B0[2][2], B1[2][2];
;     const char* cA = (const char*)g.A + (size_t)cur.g * g.gsA * 2 + (size_t)cur.pm * tstepA; const char* cB = (const char*)g.Bt + (size_t)cur.g * g.gsB * 2 + (size_t)cur.pn * tstepB;
;     S.a_ready(cur);
;     if constexpr (SP2) {
;         PG8_STAGE(PG8_SB(0, 0), cB, voffB); PG8_STAGE(PG8_SB(0, 1), cB + hstepB, voffB); PG8_STAGE(PG8_SA(0, 0), cA, voffA); PG8_STAGE(PG8_SA(0, 1), cA + hstepA, voffA);
;         if (wr == 1) PG8_BAR;
.LBB0_759:
	v_cndmask_b32_e64 v1, 0, 1, s[4:5]
	v_cmp_ne_u32_e64 s[6:7], 1, v1
	s_andn2_b64 vcc, exec, s[4:5]
	s_cmp_eq_u32 s99, 1
	s_cbranch_scc1 .LBB0_799
	s_cbranch_vccnz .LBB0_799
	v_ashrrev_i32_e32 v2, 31, v10
	v_lshrrev_b32_e32 v2, 26, v2
	v_add_u32_e32 v2, v10, v2
	v_ashrrev_i32_e32 v11, 6, v2
	v_bfe_i32 v2, v10, 27, 1
	v_lshlrev_b32_e32 v1, 4, v10
	v_lshrrev_b32_e32 v2, 22, v2
	v_add_u32_e32 v2, v1, v2
	v_and_b32_e32 v2, 0xfffffc00, v2
	v_sub_u32_e32 v2, v1, v2
	v_lshrrev_b32_e32 v3, 4, v2
	v_bitop3_b32 v2, v3, v2, 32 bitop3:0x6c
	v_ashrrev_i32_e32 v4, 31, v2
	v_lshrrev_b32_e32 v4, 26, v4
	v_lshlrev_b32_e32 v3, 3, v11
	v_add_u32_e32 v4, v2, v4
	v_and_b32_e32 v3, -16, v3
	v_ashrrev_i32_e32 v13, 6, v4
	v_and_b32_e32 v4, 0xc0, v4
	v_add_u32_e32 v3, v13, v3
	v_lshlrev_b32_e32 v5, 5, v11
	v_sub_u32_e32 v2, v2, v4
	v_mov_b32_e32 v4, 1
	v_and_b32_e32 v12, 32, v5
	v_ashrrev_i16_sdwa v2, v4, sext(v2) dst_sel:DWORD dst_unused:UNUSED_PAD src0_sel:DWORD src1_sel:BYTE_0
	v_lshlrev_b32_e32 v5, 1, v3
	v_lshrrev_b32_e32 v6, 2, v3
	v_and_b32_e32 v7, 3, v13
	s_mov_b32 s0, 0xffffe0
	v_bfe_i32 v14, v2, 0, 16
	v_and_b32_e32 v5, 24, v5
	v_and_b32_e32 v6, 4, v6
	v_and_or_b32 v7, v3, s0, v7
	s_movk_i32 s4, 0xb00
	v_add_u32_e32 v2, v12, v14
	v_or3_b32 v5, v7, v6, v5
	v_mul_lo_u32 v3, v3, s4
	v_add_lshl_u32 v138, v2, v3, 1
	v_mul_u32_u24_e32 v3, 0xb00, v5
	v_add_u32_e32 v1, 0x2000, v1
	v_add_lshl_u32 v140, v3, v2, 1
	v_ashrrev_i32_e32 v2, 31, v1
	v_lshrrev_b32_e32 v2, 22, v2
	v_add_u32_e32 v2, v1, v2
	v_ashrrev_i32_e32 v15, 10, v2
	v_mul_i32_i24_e32 v2, 0x400, v15
	v_sub_u32_e32 v1, v1, v2
	v_lshrrev_b32_e32 v2, 4, v1
	v_bitop3_b32 v1, v2, v1, 32 bitop3:0x6c
	v_ashrrev_i32_e32 v3, 31, v1
	s_add_u32 s2, s78, 0x13c00000
	v_lshrrev_b32_e32 v3, 26, v3
	s_addc_u32 s3, s79, 0
	v_lshlrev_b32_e32 v2, 3, v15
	v_add_u32_e32 v3, v1, v3
	s_add_u32 s33, s78, 0x4600000
	v_and_b32_e32 v2, -16, v2
	v_ashrrev_i32_e32 v16, 6, v3
	v_lshlrev_b32_e32 v5, 5, v15
	s_addc_u32 s36, s79, 0
	s_ashr_i32 s9, s8, 6
	v_add_u32_e32 v2, v16, v2
	v_and_b32_e32 v17, 32, v5
	v_and_b32_e32 v3, 0xc0, v3
	v_and_b32_e32 v5, 3, v16
	v_sub_u32_e32 v1, v1, v3
	v_and_or_b32 v5, v2, s0, v5
	s_ashr_i32 s10, s8, 8
	s_lshl_b32 s0, s9, 10
	s_mul_i32 s12, s51, 0x160000
	v_ashrrev_i16_sdwa v1, v4, sext(v1) dst_sel:DWORD dst_unused:UNUSED_PAD src0_sel:DWORD src1_sel:BYTE_0
	v_lshlrev_b32_e32 v3, 1, v2
	v_lshrrev_b32_e32 v4, 2, v2
	s_mul_hi_i32 s1, s51, 0x160000
	s_add_u32 s28, s33, s12
	v_bfe_i32 v18, v1, 0, 16
	v_and_b32_e32 v3, 24, v3
	v_and_b32_e32 v4, 4, v4
	s_addc_u32 s29, s36, s1
	s_add_i32 s1, s0, 0
	v_add_u32_e32 v1, v17, v18
	v_or3_b32 v3, v5, v4, v3
	v_mul_lo_u32 v2, v2, s4
	s_add_i32 m0, s1, 0x10000
	v_add_lshl_u32 v142, v1, v2, 1
	v_mul_u32_u24_e32 v2, 0xb00, v3
	global_load_lds_dwordx4 v140, s[28:29]
	s_add_i32 m0, s1, 0x12000
	v_add_lshl_u32 v144, v2, v1, 1
	s_add_u32 s12, s28, 0xb0000
	global_load_lds_dwordx4 v144, s[28:29]
	s_addc_u32 s13, s29, 0
	s_add_i32 m0, s1, 0x14000
	s_mul_i32 s11, s52, 0x160000
	global_load_lds_dwordx4 v140, s[12:13]
	s_add_i32 m0, s1, 0x16000
	s_mul_hi_i32 s5, s52, 0x160000
	s_add_u32 s26, s2, s11
	s_addc_u32 s27, s3, s5
	s_add_i32 s37, s1, 0x2000
	global_load_lds_dwordx4 v144, s[12:13]
	s_mov_b32 m0, s1
	s_add_u32 s12, s26, 0xb0000
	global_load_lds_dwordx4 v138, s[26:27]
	s_mov_b32 m0, s37
	s_addc_u32 s13, s27, 0
	s_add_i32 s38, s1, 0x4000
	global_load_lds_dwordx4 v142, s[26:27]
	s_mov_b32 m0, s38
	s_add_i32 s39, s1, 0x6000
	global_load_lds_dwordx4 v138, s[12:13]
	s_mov_b32 m0, s39
	v_mov_b32_e32 v141, 0
	global_load_lds_dwordx4 v142, s[12:13]
	v_mov_b32_e32 v145, v141
	v_mov_b32_e32 v139, v141
	v_mov_b32_e32 v143, v141
	s_cmp_eq_u32 s10, 1
	s_mov_b32 s5, 0
	v_lshl_add_u64 v[8:9], s[28:29], 0, v[140:141]
	v_lshl_add_u64 v[6:7], s[28:29], 0, v[144:145]
	v_lshl_add_u64 v[2:3], s[26:27], 0, v[138:139]
	s_cselect_b64 s[14:15], -1, 0
	s_cmp_lg_u32 s10, 1
	v_lshl_add_u64 v[4:5], s[26:27], 0, v[142:143]
	s_cbranch_scc1 .LBB0_762
	s_barrier

.LBB0_799:
	s_cmp_eq_u32 s99, 2
	s_cbranch_scc1 .Lsw8_done
	s_movk_i32 s22, 0x100
	s_movk_i32 s16, 0x100
	s_movk_i32 s8, 0x100
	v_mov_b32_e32 v14, v0
	s_and_b64 vcc, exec, s[6:7]
	v_readfirstlane_b32 s7, v14
	s_cbranch_vccnz .LBB0_828
	s_ashr_i32 s0, s96, 31
	s_lshr_b32 s1, s0, 29
	s_add_i32 s1, s96, s1
	s_and_b32 s2, s1, -8
	s_sub_i32 s2, s96, s2
	s_cmp_gt_i32 s2, -1
	s_cbranch_scc0 .LBB0_802
	s_lshl_b32 s6, s2, 6
	s_cbranch_execz .LBB0_803
	s_branch .LBB0_804

.LBB0_828:
	s_cmp_eq_u32 s99, 1
	s_cbranch_scc0 .Lsw8_done
	s_mov_b32 s99, 2
	s_branch .Lsw8_top

.LBB0_1614:
	s_cmp_lt_i32 s80, 16
	s_cselect_b64 s[0:1], -1, 0
	s_cmp_gt_i32 s81, 15
	s_cselect_b64 s[2:3], -1, 0
	s_and_b64 s[0:1], s[0:1], s[2:3]
	s_andn2_b64 vcc, exec, s[0:1]
	s_cbranch_vccnz .LBB0_1744
	s_mov_b32 s99, 0
	s_cmp_eq_u32 s82, 0x100
	s_cbranch_scc0 .Lsw15_top
	s_cmp_lt_u32 s96, 0x80
	s_cbranch_scc1 .Lsw15_top
	s_mov_b32 s99, 1

; #define PG8_STAGE(bufoff, gbase, voff) do { _Pragma("unroll") for (int _i = 0; _i < 2; ++_i) \
;         __builtin_amdgcn_global_load_lds((const unsigned*)((const char*)(gbase) + (voff)[_i]), (PG8_LAS unsigned*)(lds + (bufoff) + ldsw + _i * 8192), 16, 0, 0); } while (0)
; #define PG8_BAR __builtin_amdgcn_s_barrier()
; template <class Epi, class Sched, bool ALIGN_EPI = false, bool SP2 = false>
; __device__ __forceinline__ void gemm_phase(PG8_LAS unsigned char* lds, const Gemm g, const Sched& S, const Epi& E) {
;     int tid_ = threadIdx.x; asm volatile("" : "+v"(tid_));
;     const int tid = tid_, wid = __builtin_amdgcn_readfirstlane(tid >> 6), lane = tid & 63, wr = wid >> 2, wc = wid & 3, fr = lane & 15, fq = lane >> 4;
;     const int K = g.K, nt = K / BK;
;     unsigned voffA[2], voffB[2];
; #pragma unroll
;     for (int i = 0; i < 2; ++i) { int R, C; stage_rc(tid * 16 + i * 8192, R, C); const int Rb = Epi::PERM ? ((R & ~31) + perm32(R & 31)) : R;
;         voffA[i] = (unsigned)(R * g.lda + C) * 2u; voffB[i] = (unsigned)(Rb * g.ldb + C) * 2u; }
;     const size_t kstep = (size_t)(BK * 2);
;     const size_t hstepA = (size_t)HALF * g.lda * 2, hstepB = (size_t)HALF * g.ldb * 2;
;     const size_t tstepA = 2 * hstepA, tstepB = 2 * hstepB;
;     const unsigned ldsw = (unsigned)wid * 1024u;
;     const int aoff = lds_byte(wr * 64 + fr, fq * 8), boff = lds_byte(wc * 32 + fr, fq * 8);
;     ...
;     Unit cur, nxt; int ui = 0;
;     if (!S.next(0, cur)) return;
;     f32x4 acc[2][2][4][2];
; #pragma unroll
;     for (int a = 0; a < 2; ++a)
; #pragma unroll
;         for (int b = 0; b < 2; ++b)
; #pragma unroll
;             for (int m = 0; m < 4; ++m)
; #pragma unroll
;                 for (int n = 0; n < 2; ++n) acc[a][b][m][n] = (f32x4){0.f, 0.f, 0.f, 0.f};
;     bf16x8 At[4][2], B0[2][2], B1[2][2];
;     const char* cA = (const char*)g.A + (size_t)cur.g * g.gsA * 2 + (size_t)cur.pm * tstepA; const char* cB = (const char*)g.Bt + (size_t)cur.g * g.gsB * 2 + (size_t)cur.pn * tstepB;
;     S.a_ready(cur);
;     if constexpr (SP2) {
;         PG8_STAGE(PG8_SB(0, 0), cB, voffB); PG8_STAGE(PG8_SB(0, 1), cB + hstepB, voffB); PG8_STAGE(PG8_SA(0, 0), cA, voffA); PG8_STAGE(PG8_SA(0, 1), cA + hstepA, voffA);
;         if (wr == 1) PG8_BAR;
.LBB0_1621:
	v_cndmask_b32_e64 v1, 0, 1, s[4:5]
	v_cmp_ne_u32_e64 s[6:7], 1, v1
	s_andn2_b64 vcc, exec, s[4:5]
	s_cmp_eq_u32 s99, 1
	s_cbranch_scc1 .LBB0_1661
	s_cbranch_vccnz .LBB0_1661
	v_ashrrev_i32_e32 v2, 31, v10
	v_lshrrev_b32_e32 v2, 26, v2
	v_add_u32_e32 v2, v10, v2
	v_ashrrev_i32_e32 v11, 6, v2
	v_bfe_i32 v2, v10, 27, 1
	v_lshlrev_b32_e32 v1, 4, v10
	v_lshrrev_b32_e32 v2, 22, v2
	v_add_u32_e32 v2, v1, v2
	v_and_b32_e32 v2, 0xfffffc00, v2
	v_sub_u32_e32 v2, v1, v2
	v_lshrrev_b32_e32 v3, 4, v2
	v_bitop3_b32 v2, v3, v2, 32 bitop3:0x6c
	v_ashrrev_i32_e32 v4, 31, v2
	v_lshrrev_b32_e32 v4, 26, v4
	v_lshlrev_b32_e32 v3, 3, v11
	v_add_u32_e32 v4, v2, v4
	v_and_b32_e32 v3, -16, v3
	v_ashrrev_i32_e32 v13, 6, v4
	v_and_b32_e32 v4, 0xc0, v4
	v_add_u32_e32 v3, v13, v3
	v_lshlrev_b32_e32 v5, 5, v11
	v_sub_u32_e32 v2, v2, v4
	v_mov_b32_e32 v4, 1
	v_and_b32_e32 v12, 32, v5
	v_ashrrev_i16_sdwa v2, v4, sext(v2) dst_sel:DWORD dst_unused:UNUSED_PAD src0_sel:DWORD src1_sel:BYTE_0
	v_lshlrev_b32_e32 v5, 1, v3
	v_lshrrev_b32_e32 v6, 2, v3
	v_and_b32_e32 v7, 3, v13
	s_mov_b32 s0, 0xffffe0
	v_bfe_i32 v14, v2, 0, 16
	v_and_b32_e32 v5, 24, v5
	v_and_b32_e32 v6, 4, v6
	v_and_or_b32 v7, v3, s0, v7
	s_movk_i32 s4, 0xb00
	v_add_u32_e32 v2, v12, v14
	v_or3_b32 v5, v7, v6, v5
	v_mul_lo_u32 v3, v3, s4
	v_add_lshl_u32 v138, v2, v3, 1
	v_mul_u32_u24_e32 v3, 0xb00, v5
	v_add_u32_e32 v1, 0x2000, v1
	v_add_lshl_u32 v140, v3, v2, 1
	v_ashrrev_i32_e32 v2, 31, v1
	v_lshrrev_b32_e32 v2, 22, v2
	v_add_u32_e32 v2, v1, v2
	v_ashrrev_i32_e32 v15, 10, v2
	v_mul_i32_i24_e32 v2, 0x400, v15
	v_sub_u32_e32 v1, v1, v2
	v_lshrrev_b32_e32 v2, 4, v1
	v_bitop3_b32 v1, v2, v1, 32 bitop3:0x6c
	v_ashrrev_i32_e32 v3, 31, v1
	s_add_u32 s2, s78, 0x13c00000
	v_lshrrev_b32_e32 v3, 26, v3
	s_addc_u32 s3, s79, 0
	v_lshlrev_b32_e32 v2, 3, v15
	v_add_u32_e32 v3, v1, v3
	s_add_u32 s33, s78, 0x4b80000
	v_and_b32_e32 v2, -16, v2
	v_ashrrev_i32_e32 v16, 6, v3
	v_lshlrev_b32_e32 v5, 5, v15
	s_addc_u32 s36, s79, 0
	s_ashr_i32 s9, s8, 6
	v_add_u32_e32 v2, v16, v2
	v_and_b32_e32 v17, 32, v5
	v_and_b32_e32 v3, 0xc0, v3
	v_and_b32_e32 v5, 3, v16
	v_sub_u32_e32 v1, v1, v3
	v_and_or_b32 v5, v2, s0, v5
	s_ashr_i32 s10, s8, 8
	s_lshl_b32 s0, s9, 10
	s_mul_i32 s12, s51, 0x160000
	v_ashrrev_i16_sdwa v1, v4, sext(v1) dst_sel:DWORD dst_unused:UNUSED_PAD src0_sel:DWORD src1_sel:BYTE_0
	v_lshlrev_b32_e32 v3, 1, v2
	v_lshrrev_b32_e32 v4, 2, v2
	s_mul_hi_i32 s1, s51, 0x160000
	s_add_u32 s28, s33, s12
	v_bfe_i32 v18, v1, 0, 16
	v_and_b32_e32 v3, 24, v3
	v_and_b32_e32 v4, 4, v4
	s_addc_u32 s29, s36, s1
	s_add_i32 s1, s0, 0
	v_add_u32_e32 v1, v17, v18
	v_or3_b32 v3, v5, v4, v3
	v_mul_lo_u32 v2, v2, s4
	s_add_i32 m0, s1, 0x10000
	v_add_lshl_u32 v142, v1, v2, 1
	v_mul_u32_u24_e32 v2, 0xb00, v3
	global_load_lds_dwordx4 v140, s[28:29]
	s_add_i32 m0, s1, 0x12000
	v_add_lshl_u32 v144, v2, v1, 1
	s_add_u32 s12, s28, 0xb0000
	global_load_lds_dwordx4 v144, s[28:29]
	s_addc_u32 s13, s29, 0
	s_add_i32 m0, s1, 0x14000
	s_mul_i32 s11, s52, 0x160000
	global_load_lds_dwordx4 v140, s[12:13]
	s_add_i32 m0, s1, 0x16000
	s_mul_hi_i32 s5, s52, 0x160000
	s_add_u32 s26, s2, s11
	s_addc_u32 s27, s3, s5
	s_add_i32 s37, s1, 0x2000
	global_load_lds_dwordx4 v144, s[12:13]
	s_mov_b32 m0, s1
	s_add_u32 s12, s26, 0xb0000
	global_load_lds_dwordx4 v138, s[26:27]
	s_mov_b32 m0, s37
	s_addc_u32 s13, s27, 0
	s_add_i32 s38, s1, 0x4000
	global_load_lds_dwordx4 v142, s[26:27]
	s_mov_b32 m0, s38
	s_add_i32 s39, s1, 0x6000
	global_load_lds_dwordx4 v138, s[12:13]
	s_mov_b32 m0, s39
	v_mov_b32_e32 v141, 0
	global_load_lds_dwordx4 v142, s[12:13]
	v_mov_b32_e32 v145, v141
	v_mov_b32_e32 v139, v141
	v_mov_b32_e32 v143, v141
	s_cmp_eq_u32 s10, 1
	s_mov_b32 s5, 0
	v_lshl_add_u64 v[8:9], s[28:29], 0, v[140:141]
	v_lshl_add_u64 v[6:7], s[28:29], 0, v[144:145]
	v_lshl_add_u64 v[2:3], s[26:27], 0, v[138:139]
	s_cselect_b64 s[14:15], -1, 0
	s_cmp_lg_u32 s10, 1
	v_lshl_add_u64 v[4:5], s[26:27], 0, v[142:143]
	s_cbranch_scc1 .LBB0_1624
	s_barrier
